# prep rmsnorm row sum: 6-hop LDS bpermute chain replaced by DPP + permlane16/32 swap all-reduce
# speedup vs baseline: 1.0022x; 1.0002x over previous
.LBB0_9:
	global_load_dwordx4 v[22:25], v[12:13], off offset:-4096
	global_load_dwordx4 v[26:29], v[12:13], off offset:-3072
	global_load_dwordx4 v[30:33], v[12:13], off offset:-2048
	global_load_dwordx4 v[34:37], v[12:13], off offset:-1024
	global_load_dwordx4 v[38:41], v[12:13], off
	global_load_dwordx4 v[42:45], v[12:13], off offset:1024
	global_load_dwordx4 v[46:49], v[12:13], off offset:2048
	global_load_dwordx4 v[50:53], v[12:13], off offset:3072
	global_load_dwordx4 v[54:57], v[0:1], off
	v_add_u32_e32 v21, s80, v21
	v_lshl_add_u64 v[12:13], v[12:13], 0, s[8:9]
	s_waitcnt vmcnt(8)
	v_pk_mul_f32 v[60:61], v[22:23], v[22:23]
	s_waitcnt vmcnt(7)
	v_pk_mul_f32 v[64:65], v[26:27], v[26:27]
	v_pk_mul_f32 v[58:59], v[24:25], v[24:25]
	v_pk_mul_f32 v[62:63], v[28:29], v[28:29]
	s_waitcnt vmcnt(6)
	v_pk_mul_f32 v[68:69], v[30:31], v[30:31]
	v_add_f32_e32 v90, v64, v65
	v_add_f32_e32 v91, v60, v61
	v_pk_mul_f32 v[66:67], v[32:33], v[32:33]
	s_waitcnt vmcnt(5)
	v_pk_mul_f32 v[72:73], v[34:35], v[34:35]
	s_waitcnt vmcnt(4)
	v_mov_b32_e32 v80, v39
	s_waitcnt vmcnt(3)
	v_mov_b32_e32 v81, v43
	v_add_f32_e32 v68, v68, v69
	v_add_f32_e32 v62, v90, v62
	v_add_f32_e32 v58, v91, v58
	v_pk_mul_f32 v[70:71], v[36:37], v[36:37]
	v_mov_b32_e32 v78, v38
	v_mov_b32_e32 v79, v42
	v_pk_mul_f32 v[80:81], v[80:81], v[80:81]
	v_add_f32_e32 v69, v72, v73
	v_add_f32_e32 v66, v68, v66
	v_add_f32_e32 v62, v62, v63
	v_add_f32_e32 v63, v58, v59
	v_mov_b32_e32 v74, v40
	v_mov_b32_e32 v75, v44
	s_waitcnt vmcnt(2)
	v_mov_b32_e32 v88, v47
	s_waitcnt vmcnt(1)
	v_mov_b32_e32 v89, v51
	v_pk_fma_f32 v[60:61], v[78:79], v[78:79], v[80:81]
	v_add_f32_e32 v68, v69, v70
	v_add_f32_e32 v66, v66, v67
	v_add_f32_e32 v62, v63, v62
	v_mov_b32_e32 v76, v41
	v_mov_b32_e32 v77, v45
	v_mov_b32_e32 v86, v46
	v_mov_b32_e32 v87, v50
	v_pk_mul_f32 v[88:89], v[88:89], v[88:89]
	v_pk_fma_f32 v[60:61], v[74:75], v[74:75], v[60:61]
	v_add_f32_e32 v67, v68, v71
	v_add_f32_e32 v62, v62, v66
	v_mov_b32_e32 v82, v48
	v_mov_b32_e32 v83, v52
	v_pk_fma_f32 v[64:65], v[86:87], v[86:87], v[88:89]
	v_pk_fma_f32 v[58:59], v[76:77], v[76:77], v[60:61]
	v_add_f32_e32 v62, v62, v67
	v_mov_b32_e32 v84, v49
	v_mov_b32_e32 v85, v53
	v_pk_fma_f32 v[64:65], v[82:83], v[82:83], v[64:65]
	v_add_f32_e32 v58, v62, v58
	v_pk_fma_f32 v[60:61], v[84:85], v[84:85], v[64:65]
	v_add_f32_e32 v58, v58, v59
	v_add_f32_e32 v58, v58, v60
	v_add_f32_e32 v58, v58, v61
	s_nop 1
	v_add_f32_dpp v58, v58, v58 quad_perm:[1,0,3,2] row_mask:0xf bank_mask:0xf
	s_nop 1
	v_add_f32_dpp v58, v58, v58 quad_perm:[2,3,0,1] row_mask:0xf bank_mask:0xf
	s_nop 1
	v_add_f32_dpp v58, v58, v58 row_half_mirror row_mask:0xf bank_mask:0xf
	s_nop 1
	v_add_f32_dpp v58, v58, v58 row_mirror row_mask:0xf bank_mask:0xf
	s_nop 1
	v_mov_b32_e32 v59, v58
	s_nop 1
	v_permlane16_swap_b32 v59, v58
	v_add_f32_e32 v58, v58, v59
	v_mov_b32_e32 v59, v58
	s_nop 1
	v_permlane32_swap_b32 v59, v58
	v_add_f32_e32 v58, v58, v59
	v_fmamk_f32 v58, v58, 0x3a000000, v20
	v_mul_f32_e32 v59, 0x4b800000, v58
	v_cmp_gt_f32_e32 vcc, s0, v58
	s_nop 1
	v_cndmask_b32_e32 v58, v58, v59, vcc
	v_rsq_f32_e32 v58, v58
	s_nop 0
	v_mul_f32_e32 v59, 0x45800000, v58
	v_cndmask_b32_e32 v58, v58, v59, vcc
	v_pk_mul_f32 v[22:23], v[22:23], v[58:59] op_sel_hi:[1,0]
	v_pk_mul_f32 v[24:25], v[24:25], v[58:59] op_sel_hi:[1,0]
	s_waitcnt vmcnt(0)
	v_pk_mul_f32 v[22:23], v[54:55], v[22:23]
	v_pk_mul_f32 v[24:25], v[56:57], v[24:25]
	v_cvt_pk_bf16_f32 v22, v22, v23
	v_cvt_pk_bf16_f32 v23, v24, v25
	global_store_dwordx2 v[10:11], v[22:23], off offset:-2048
	global_load_dwordx4 v[22:25], v[0:1], off offset:1024
	v_pk_mul_f32 v[26:27], v[26:27], v[58:59] op_sel_hi:[1,0]
	v_pk_mul_f32 v[28:29], v[28:29], v[58:59] op_sel_hi:[1,0]
	v_cmp_lt_i32_e32 vcc, s1, v21
	s_or_b64 s[14:15], vcc, s[14:15]
	s_waitcnt vmcnt(0)
	v_pk_mul_f32 v[22:23], v[22:23], v[26:27]
	v_pk_mul_f32 v[24:25], v[24:25], v[28:29]
	v_cvt_pk_bf16_f32 v22, v22, v23
	v_cvt_pk_bf16_f32 v23, v24, v25
	global_store_dwordx2 v[10:11], v[22:23], off offset:-1536
	global_load_dwordx4 v[22:25], v[0:1], off offset:2048
	v_pk_mul_f32 v[26:27], v[30:31], v[58:59] op_sel_hi:[1,0]
	v_pk_mul_f32 v[28:29], v[32:33], v[58:59] op_sel_hi:[1,0]
	s_waitcnt vmcnt(0)
	v_pk_mul_f32 v[22:23], v[26:27], v[22:23]
	v_pk_mul_f32 v[24:25], v[28:29], v[24:25]
	v_cvt_pk_bf16_f32 v22, v22, v23
	v_cvt_pk_bf16_f32 v23, v24, v25
	global_store_dwordx2 v[10:11], v[22:23], off offset:-1024
	global_load_dwordx4 v[22:25], v[0:1], off offset:3072
	v_pk_mul_f32 v[26:27], v[34:35], v[58:59] op_sel_hi:[1,0]
	v_pk_mul_f32 v[28:29], v[36:37], v[58:59] op_sel_hi:[1,0]
	s_waitcnt vmcnt(0)
	v_pk_mul_f32 v[22:23], v[26:27], v[22:23]
	v_pk_mul_f32 v[24:25], v[28:29], v[24:25]
	v_cvt_pk_bf16_f32 v22, v22, v23
	v_cvt_pk_bf16_f32 v23, v24, v25
	global_store_dwordx2 v[10:11], v[22:23], off offset:-512
	global_load_dwordx4 v[22:25], v[2:3], off
	v_pk_mul_f32 v[26:27], v[38:39], v[58:59] op_sel_hi:[1,0]
	v_pk_mul_f32 v[28:29], v[40:41], v[58:59] op_sel_hi:[1,0]
	s_waitcnt vmcnt(0)
	v_pk_mul_f32 v[22:23], v[26:27], v[22:23]
	v_pk_mul_f32 v[24:25], v[28:29], v[24:25]
	v_cvt_pk_bf16_f32 v22, v22, v23
	v_cvt_pk_bf16_f32 v23, v24, v25
	global_store_dwordx2 v[10:11], v[22:23], off
	global_load_dwordx4 v[22:25], v[4:5], off
	v_pk_mul_f32 v[26:27], v[42:43], v[58:59] op_sel_hi:[1,0]
	v_pk_mul_f32 v[28:29], v[44:45], v[58:59] op_sel_hi:[1,0]
	s_waitcnt vmcnt(0)
	v_pk_mul_f32 v[22:23], v[26:27], v[22:23]
	v_pk_mul_f32 v[24:25], v[28:29], v[24:25]
	v_cvt_pk_bf16_f32 v22, v22, v23
	v_cvt_pk_bf16_f32 v23, v24, v25
	global_store_dwordx2 v[10:11], v[22:23], off offset:512
	global_load_dwordx4 v[22:25], v[6:7], off
	v_pk_mul_f32 v[26:27], v[46:47], v[58:59] op_sel_hi:[1,0]
	v_pk_mul_f32 v[28:29], v[48:49], v[58:59] op_sel_hi:[1,0]
	s_waitcnt vmcnt(0)
	v_pk_mul_f32 v[22:23], v[26:27], v[22:23]
	v_pk_mul_f32 v[24:25], v[28:29], v[24:25]
	v_cvt_pk_bf16_f32 v22, v22, v23
	v_cvt_pk_bf16_f32 v23, v24, v25
	global_store_dwordx2 v[10:11], v[22:23], off offset:1024
	global_load_dwordx4 v[22:25], v[8:9], off
	v_pk_mul_f32 v[26:27], v[50:51], v[58:59] op_sel_hi:[1,0]
	v_pk_mul_f32 v[28:29], v[52:53], v[58:59] op_sel_hi:[1,0]
	s_waitcnt vmcnt(0)
	v_pk_mul_f32 v[22:23], v[26:27], v[22:23]
	v_pk_mul_f32 v[24:25], v[28:29], v[24:25]
	v_cvt_pk_bf16_f32 v22, v22, v23
	v_cvt_pk_bf16_f32 v23, v24, v25
	global_store_dwordx2 v[10:11], v[22:23], off offset:1536
	v_lshl_add_u64 v[10:11], v[10:11], 0, s[10:11]
	s_andn2_b64 exec, exec, s[14:15]
	s_cbranch_execnz .LBB0_9
